# m1fc+m1c: M1 K/V staging pieces per lane made adjacent (line fetched by 4 waves instead of 8), 4 tile loads issued together, per-item wv barrier dropped
# baseline (speedup 1.0000x reference)
;   __host__ __device__ __forceinline__ bf16_t* ACT() const { return (bf16_t*)(wsl() + OFF_ACT); }
; __device__ __forceinline__ int obid() { int t = blockIdx.x; asm volatile("" : "+s"(t)); return t; }
; __device__ __forceinline__ void m1_phase(const Params& p, char* smem) {
;     ...
;   bf16_t* Kt = (bf16_t*)smem;
;   bf16_t* Vt = Kt + 128 * 72;
;   float* wv = (float*)(Vt + 128 * 72);
;   for (int it = obid(); it < NCHAIN * NCHUNK; it += gridDim.x) {
;     int ci = it / NCHUNK, j = it - ci * NCHUNK;
;     int dir = ci & 1, h = (ci >> 1) & 3, b = ci >> 3;
;     int rowbase = b * TPB;
;     ...
;     for (int i = 0; i < 2; ++i) {
;       int idx = tid + i * NTHR;
;       int r = idx & 63, fc = (idx >> 6) * 8;
;       int row = rowbase + mchunk_tok(dir, j, r);
;       const bf16_t* src = p.ACT() + (size_t)row * PW;
;       uint4 kv = *(const uint4*)(src + 1184 + h * 128 + fc);
;       uint4 vv = *(const uint4*)(src + 1696 + h * 128 + fc);
;       float wr = wv[r];
.LBB0_765:
	s_or_b64 exec, exec, s[4:5]
	s_mov_b32 s56, s82
	s_cmpk_gt_i32 s56, 0x83f
	s_cbranch_scc1 .LBB0_779
	s_waitcnt lgkmcnt(0)
	v_and_b32_e32 v1, 15, v8
	v_and_b32_e32 v0, 48, v10
	v_lshl_or_b32 v2, v18, 4, v1
	v_add_u32_e32 v0, 0, v0
	s_movk_i32 s4, 0x90
	v_mad_u64_u32 v[12:13], s[2:3], v2, s4, v[0:1]
	v_mul_lo_u32 v2, v8, s4
	v_add_u32_e32 v13, 0, v2
	v_lshrrev_b32_e32 v2, 6, v8
	v_lshlrev_b32_e32 v2, 4, v2
	v_and_b32_e32 v14, -8, v2
	s_movk_i32 s4, 0x48
	v_mul_lo_u32 v3, v14, s4
	v_lshl_add_u32 v11, v10, 2, 0
	v_or_b32_e32 v3, v3, v10
	v_or_b32_e32 v2, 7, v2
	v_lshl_add_u32 v38, v3, 1, 0
	v_mad_u64_u32 v[2:3], s[2:3], v2, s4, v[10:11]
	v_lshl_add_u32 v39, v2, 1, 0
	v_lshrrev_b32_e32 v2, 6, v8
	v_lshlrev_b32_e32 v2, 4, v2
	v_add_u32_e32 v2, 8, v2
	v_and_b32_e32 v16, -8, v2
	v_mul_lo_u32 v3, v16, s4
	v_or_b32_e32 v3, v3, v10
	v_or_b32_e32 v2, 7, v2
	v_lshl_add_u32 v40, v3, 1, 0
	v_mad_u64_u32 v[2:3], s[2:3], v2, s4, v[10:11]
	s_load_dwordx2 s[2:3], s[0:1], 0xf0
	v_lshl_add_u32 v41, v2, 1, 0
	v_lshlrev_b32_e32 v2, 5, v10
	v_lshlrev_b32_e32 v3, 11, v18
	s_movk_i32 s4, 0x600
	s_waitcnt lgkmcnt(0)
	s_add_u32 s58, s2, 0x7290000
	s_addc_u32 s59, s3, 0
	v_ashrrev_i32_e32 v9, 31, v8
	v_and_or_b32 v2, v2, s4, v3
	s_add_u32 s8, s2, 0xcd50000
	v_mul_u32_u24_e32 v4, 0x90, v1
	v_ashrrev_i32_e32 v19, 31, v2
	v_or_b32_e32 v20, v1, v2
	s_addc_u32 s9, s3, 0
	v_lshl_add_u64 v[2:3], v[8:9], 2, s[2:3]
	s_mov_b64 s[2:3], 0x113b7000
	v_cmp_gt_u32_e64 s[40:41], 64, v8
	v_cmp_eq_u32_e64 s[42:43], 0, v10
	v_cmp_gt_i32_e64 s[44:45], s85, v8
	v_cmp_gt_u32_e64 s[46:47], 2, v10
	v_cmp_gt_u32_e64 s[48:49], 4, v10
	v_cmp_gt_u32_e64 s[50:51], 8, v10
	v_cmp_gt_u32_e64 s[52:53], 16, v10
	v_cmp_gt_u32_e64 s[54:55], 32, v10
	v_ashrrev_i32_e32 v15, 31, v14
	v_ashrrev_i32_e32 v17, 31, v16
	v_ashrrev_i32_e32 v21, 31, v20
	v_lshl_add_u64 v[22:23], v[2:3], 0, s[2:3]
	v_mov_b32_e32 v18, v20
	v_or_b32_e32 v24, 16, v20
	v_mov_b32_e32 v25, v19
	v_or_b32_e32 v26, 32, v20
	v_mov_b32_e32 v27, v19
	v_or_b32_e32 v28, 48, v20
	v_mov_b32_e32 v29, v19
	v_or_b32_e32 v30, 64, v20
	v_mov_b32_e32 v31, v19
	v_or_b32_e32 v32, 0x50, v20
	v_mov_b32_e32 v33, v19
	v_or_b32_e32 v34, 0x60, v20
	v_mov_b32_e32 v35, v19
	v_or_b32_e32 v36, 0x70, v20
	v_mov_b32_e32 v37, v19
	v_add_u32_e32 v9, v0, v4
	v_lshrrev_b32_e32 v79, 6, v8
	v_lshrrev_b32_e32 v76, 4, v10
	v_lshl_add_u32 v76, v79, 2, v76
	v_mul_u32_u24_e32 v76, 0x440, v76
	v_and_b32_e32 v77, 15, v10
	v_lshl_add_u32 v76, v77, 1, v76
	v_add_u32_e32 v76, 0x9900, v76
	v_lshrrev_b32_e32 v78, 4, v10
	v_lshl_add_u32 v78, v79, 4, v78
	v_and_b32_e32 v79, 15, v10
	v_mul_u32_u24_e32 v77, 0x110, v78
	v_lshl_add_u32 v77, v79, 4, v77
	v_add_u32_e32 v77, 0x9900, v77
	v_lshlrev_b32_e32 v78, 8, v78
	v_lshl_add_u32 v78, v79, 4, v78
	v_mov_b32_e32 v79, 0
	s_mov_b32 s61, 0
	v_readfirstlane_b32 s62, v8
	s_lshr_b32 s62, s62, 6
	s_mul_i32 s63, s62, s80
	s_add_i32 s63, s63, s56
	s_lshl_b32 s64, s62, 8

;   __host__ __device__ __forceinline__ float* G() const { return (float*)(wsl() + OFF_G); }
;   __host__ __device__ __forceinline__ float* mloc() const { return (float*)(wsl() + OFF_MLOC); }
;   __host__ __device__ __forceinline__ float* bend() const { return (float*)(wsl() + OFF_BEND); }
; __device__ __forceinline__ float logsigmoidf_(float x) { return fminf(x, 0.0f) - log1pf(__expf(-fabsf(x))); }
; __device__ __forceinline__ void m1_phase(const Params& p, char* smem) {
;     ...
;     if (w == 0) {
;       int row = rowbase + mchunk_tok(dir, j, lane);
;       float gi = p.G()[(size_t)row * 16 + (2 * dir) * 4 + h] + p.mlstm_gate_b[(2 * dir) * 4 + h];
;       float gf = p.G()[(size_t)row * 16 + (2 * dir + 1) * 4 + h] + p.mlstm_gate_b[(2 * dir + 1) * 4 + h];
;       float bsum = logsigmoidf_(gf);
; #pragma unroll
;       for (int o = 1; o < 64; o <<= 1) { float t = __shfl_up(bsum, o); if (lane >= o) bsum += t; }
;       float be = __shfl(bsum, 63);
;       float gg = be - bsum + gi;
;       float ml = wave_max(gg);
;       wv[lane] = __expf(gg - ml);
;       if (lane == 0) { p.mloc()[it] = ml; p.bend()[it] = be; }
;     }
;     __syncthreads();
.Lm1pre_done:
	s_waitcnt lgkmcnt(0)
	s_barrier
	s_branch .LBB0_768

;   __host__ __device__ __forceinline__ bf16_t* ACT() const { return (bf16_t*)(wsl() + OFF_ACT); }
; __device__ __forceinline__ float bf2f(bf16_t h) { return __uint_as_float(((uint32_t)h) << 16); }
; __device__ __forceinline__ void m1_phase(const Params& p, char* smem) {
;     ...
;     for (int i = 0; i < 2; ++i) {
;       int idx = tid + i * NTHR;
;       int r = idx & 63, fc = (idx >> 6) * 8;
;       int row = rowbase + mchunk_tok(dir, j, r);
;       const bf16_t* src = p.ACT() + (size_t)row * PW;
;       uint4 kv = *(const uint4*)(src + 1184 + h * 128 + fc);
;       uint4 vv = *(const uint4*)(src + 1696 + h * 128 + fc);
;       float wr = wv[r];
;       const bf16_t* ke = (const bf16_t*)&kv; const bf16_t* ve = (const bf16_t*)&vv;
; #pragma unroll
;       for (int e = 0; e < 8; ++e) {
;         Kt[(fc + e) * 72 + r] = ke[e];
;         Vt[(fc + e) * 72 + r] = f2bf(bf2f(ve[e]) * wr);
;       }
;     }
.LBB0_775:
	s_cmp_eq_u32 s13, 0
	s_cselect_b64 vcc, -1, 0
	s_cmp_gt_i32 s12, 3
	s_cselect_b32 s68, 0x87, 3
	s_sub_i32 s68, s68, s12
	s_lshl_b32 s68, s68, 6
	v_bitop3_b32 v136, s68, 63, v10 bitop3:0x36
	v_lshl_or_b32 v137, s12, 6, v10
	v_cndmask_b32_e32 v136, v136, v137, vcc
	v_add_u32_e32 v138, s11, v136
	v_mov_b64_e32 v[136:137], s[58:59]
	v_mad_i64_i32 v[136:137], s[68:69], v138, s84, v[136:137]
	s_lshl_b32 s30, s10, 8
	v_lshl_add_u64 v[140:141], v[136:137], 0, s[30:31]
	v_lshl_add_u64 v[142:143], v[14:15], 1, v[140:141]
	v_lshl_add_u64 v[144:145], v[16:17], 1, v[140:141]
	global_load_dwordx4 v[120:123], v[142:143], off offset:2368
	global_load_dwordx4 v[124:127], v[142:143], off offset:3392
	global_load_dwordx4 v[128:131], v[144:145], off offset:2368
	global_load_dwordx4 v[132:135], v[144:145], off offset:3392
	s_cmp_eq_u32 s13, 0
	s_cselect_b64 vcc, -1, 0
	s_cmp_gt_i32 s12, 3
	s_cselect_b32 s2, 0x87, 3
	s_sub_i32 s2, s2, s12
	s_lshl_b32 s2, s2, 6
	v_bitop3_b32 v0, s2, 63, v10 bitop3:0x36
	v_lshl_or_b32 v1, s12, 6, v10
	v_cndmask_b32_e32 v0, v0, v1, vcc
	v_add_u32_e32 v2, s11, v0
	v_mov_b64_e32 v[0:1], s[58:59]
	v_mad_i64_i32 v[0:1], s[2:3], v2, s84, v[0:1]
	s_lshl_b32 s30, s10, 8
	v_lshl_add_u64 v[44:45], v[0:1], 0, s[30:31]
	v_lshl_add_u64 v[4:5], v[14:15], 1, v[44:45]
	v_add_u32_e32 v74, s61, v11
	ds_read_b32 v42, v74 offset:36864
	s_ashr_i32 s57, s56, 31
	s_lshl_b64 s[2:3], s[56:57], 15
	s_add_u32 s4, s8, s2
	s_addc_u32 s5, s9, s3
	s_waitcnt vmcnt(3)
	ds_write_b16 v38, v120
	s_waitcnt vmcnt(2)
	v_lshlrev_b32_e32 v43, 16, v124
	s_waitcnt lgkmcnt(1)
	v_mul_f32_e32 v43, v42, v43
	v_bfe_u32 v46, v43, 16, 1
	v_add3_u32 v43, v43, v46, s28
	ds_write_b16_d16_hi v38, v43 offset:18432
	ds_write_b16_d16_hi v38, v120 offset:144
	v_and_b32_e32 v0, 0xffff0000, v124
	v_mul_f32_e32 v0, v42, v0
	v_bfe_u32 v4, v0, 16, 1
	v_add3_u32 v0, v0, v4, s28
	ds_write_b16_d16_hi v38, v0 offset:18576
	ds_write_b16 v38, v121 offset:288
	v_lshlrev_b32_e32 v0, 16, v125
	v_mul_f32_e32 v0, v42, v0
	v_bfe_u32 v4, v0, 16, 1
	v_add3_u32 v0, v0, v4, s28
	ds_write_b16_d16_hi v38, v0 offset:18720
	ds_write_b16_d16_hi v38, v121 offset:432
	v_and_b32_e32 v0, 0xffff0000, v125
	v_mul_f32_e32 v0, v42, v0
	v_bfe_u32 v1, v0, 16, 1
	v_add3_u32 v0, v0, v1, s28
	ds_write_b16_d16_hi v38, v0 offset:18864
	ds_write_b16 v38, v122 offset:576
	v_lshlrev_b32_e32 v0, 16, v126
	v_mul_f32_e32 v0, v42, v0
	v_bfe_u32 v1, v0, 16, 1
	v_add3_u32 v0, v0, v1, s28
	ds_write_b16_d16_hi v38, v0 offset:19008
	ds_write_b16_d16_hi v38, v122 offset:720
	v_and_b32_e32 v0, 0xffff0000, v126
	v_mul_f32_e32 v0, v42, v0
	v_bfe_u32 v1, v0, 16, 1
	v_add3_u32 v0, v0, v1, s28
	ds_write_b16_d16_hi v38, v0 offset:19152
	ds_write_b16 v38, v123 offset:864
	v_lshlrev_b32_e32 v0, 16, v127
	v_mul_f32_e32 v0, v42, v0
	v_bfe_u32 v1, v0, 16, 1
	v_add3_u32 v0, v0, v1, s28
	ds_write_b16_d16_hi v38, v0 offset:19296
	ds_write_b16_d16_hi v39, v123
	v_and_b32_e32 v0, 0xffff0000, v127
	v_mul_f32_e32 v0, v42, v0
	v_bfe_u32 v1, v0, 16, 1
	v_add3_u32 v0, v0, v1, s28
	ds_write_b16_d16_hi v39, v0 offset:18432
	v_lshl_add_u64 v[4:5], v[16:17], 1, v[44:45]
	s_waitcnt vmcnt(1)
	ds_write_b16 v40, v128
	s_waitcnt vmcnt(0)
	v_lshlrev_b32_e32 v43, 16, v132
	v_mul_f32_e32 v43, v42, v43
	v_bfe_u32 v44, v43, 16, 1
	v_add3_u32 v43, v43, v44, s28
	ds_write_b16_d16_hi v40, v43 offset:18432
	ds_write_b16_d16_hi v40, v128 offset:144
	v_and_b32_e32 v0, 0xffff0000, v132
	v_mul_f32_e32 v0, v42, v0
	v_bfe_u32 v4, v0, 16, 1
	v_add3_u32 v0, v0, v4, s28
	ds_write_b16_d16_hi v40, v0 offset:18576
	ds_write_b16 v40, v129 offset:288
	v_lshlrev_b32_e32 v0, 16, v133
	v_mul_f32_e32 v0, v42, v0
	v_bfe_u32 v4, v0, 16, 1
	v_add3_u32 v0, v0, v4, s28
	ds_write_b16_d16_hi v40, v0 offset:18720
	ds_write_b16_d16_hi v40, v129 offset:432
	v_and_b32_e32 v0, 0xffff0000, v133
	v_mul_f32_e32 v0, v42, v0
	v_bfe_u32 v1, v0, 16, 1
	v_add3_u32 v0, v0, v1, s28
	ds_write_b16_d16_hi v40, v0 offset:18864
	ds_write_b16 v40, v130 offset:576
	v_lshlrev_b32_e32 v0, 16, v134
	v_mul_f32_e32 v0, v42, v0
	v_bfe_u32 v1, v0, 16, 1
	v_add3_u32 v0, v0, v1, s28
	ds_write_b16_d16_hi v40, v0 offset:19008
	ds_write_b16_d16_hi v40, v130 offset:720
	v_and_b32_e32 v0, 0xffff0000, v134
	v_mul_f32_e32 v0, v42, v0
	v_bfe_u32 v1, v0, 16, 1
	v_add3_u32 v0, v0, v1, s28
	ds_write_b16_d16_hi v40, v0 offset:19152
	ds_write_b16 v40, v131 offset:864
	v_lshlrev_b32_e32 v0, 16, v135
	v_mul_f32_e32 v0, v42, v0
	v_bfe_u32 v1, v0, 16, 1
	v_add3_u32 v0, v0, v1, s28
	ds_write_b16_d16_hi v40, v0 offset:19296
	ds_write_b16_d16_hi v41, v131
	v_and_b32_e32 v0, 0xffff0000, v135
	v_mul_f32_e32 v0, v42, v0
	v_bfe_u32 v1, v0, 16, 1
	v_add3_u32 v0, v0, v1, s28
	ds_write_b16_d16_hi v41, v0 offset:18432
	s_waitcnt lgkmcnt(0)
	s_barrier
;   __host__ __device__ __forceinline__ bf16_t* R() const { return (bf16_t*)(wsl() + OFF_R); }
; #define MFMA16(a, b, c) __builtin_amdgcn_mfma_f32_16x16x32_bf16(a, b, c, 0, 0, 0)
; __device__ __forceinline__ void m1_phase(const Params& p, char* smem) {
;     ...
;     f32x4 acc[8];
; #pragma unroll
;     for (int ni = 0; ni < 8; ++ni) acc[ni] = (f32x4){0.f, 0.f, 0.f, 0.f};
; #pragma unroll
;     for (int ks = 0; ks < 2; ++ks) {
;       bf16x8 a = *(const bf16x8*)(Vt + (w * 16 + fr) * 72 + ks * 32 + fq * 8);
; #pragma unroll
;       for (int ni = 0; ni < 8; ++ni) {
;         bf16x8 bb = *(const bf16x8*)(Kt + (ni * 16 + fr) * 72 + ks * 32 + fq * 8);
;         acc[ni] = MFMA16(a, bb, acc[ni]);
;       }
;     }
;     bf16_t* dC = p.R() + (size_t)it * 16384;
; #pragma unroll
;     for (int ni = 0; ni < 8; ++ni)
; #pragma unroll
;       for (int jj = 0; jj < 4; ++jj) dC[(w * 16 + fq * 4 + jj) * 128 + ni * 16 + fr] = f2bf(acc[ni][jj]);
;     if (tid < 128) {
	ds_read_b128 v[0:3], v12 offset:18432
	ds_read_b128 v[4:7], v9
	ds_read_b128 v[42:45], v9 offset:2304
	ds_read_b128 v[46:49], v9 offset:4608
	ds_read_b128 v[50:53], v9 offset:6912
	ds_read_b128 v[54:57], v9 offset:9216
	ds_read_b128 v[58:61], v9 offset:11520
	ds_read_b128 v[62:65], v9 offset:13824
	ds_read_b128 v[66:69], v9 offset:16128
	s_waitcnt lgkmcnt(7)
	v_mfma_f32_16x16x32_bf16 v[4:7], v[0:3], v[4:7], 0
	s_waitcnt lgkmcnt(6)
	v_mfma_f32_16x16x32_bf16 v[42:45], v[0:3], v[42:45], 0
	s_waitcnt lgkmcnt(5)
	v_mfma_f32_16x16x32_bf16 v[46:49], v[0:3], v[46:49], 0
	s_waitcnt lgkmcnt(4)
	v_mfma_f32_16x16x32_bf16 v[50:53], v[0:3], v[50:53], 0
	s_waitcnt lgkmcnt(3)
	v_mfma_f32_16x16x32_bf16 v[54:57], v[0:3], v[54:57], 0
	s_waitcnt lgkmcnt(2)
	v_mfma_f32_16x16x32_bf16 v[58:61], v[0:3], v[58:61], 0
	s_waitcnt lgkmcnt(1)
	v_mfma_f32_16x16x32_bf16 v[62:65], v[0:3], v[62:65], 0
	s_waitcnt lgkmcnt(0)
	v_mfma_f32_16x16x32_bf16 v[0:3], v[0:3], v[66:69], 0
	ds_read_b128 v[66:69], v12 offset:18496
	ds_read_b128 v[70:73], v9 offset:64
	s_waitcnt lgkmcnt(0)
	v_mfma_f32_16x16x32_bf16 v[4:7], v[66:69], v[70:73], v[4:7]
	ds_read_b128 v[70:73], v9 offset:2368
	s_waitcnt lgkmcnt(0)
	v_mfma_f32_16x16x32_bf16 v[42:45], v[66:69], v[70:73], v[42:45]
	ds_read_b128 v[70:73], v9 offset:4672
	s_waitcnt lgkmcnt(0)
	v_mfma_f32_16x16x32_bf16 v[46:49], v[66:69], v[70:73], v[46:49]
	ds_read_b128 v[70:73], v9 offset:6976
	s_waitcnt lgkmcnt(0)
	v_mfma_f32_16x16x32_bf16 v[50:53], v[66:69], v[70:73], v[50:53]
	ds_read_b128 v[70:73], v9 offset:9280
	s_waitcnt lgkmcnt(0)
	v_mfma_f32_16x16x32_bf16 v[54:57], v[66:69], v[70:73], v[54:57]
	ds_read_b128 v[70:73], v9 offset:11584
	s_waitcnt lgkmcnt(0)
	v_mfma_f32_16x16x32_bf16 v[58:61], v[66:69], v[70:73], v[58:61]
	ds_read_b128 v[70:73], v9 offset:13888
	s_waitcnt lgkmcnt(0)
	v_mfma_f32_16x16x32_bf16 v[62:65], v[66:69], v[70:73], v[62:65]
	ds_read_b128 v[70:73], v9 offset:16192
	s_waitcnt lgkmcnt(0)
	v_mfma_f32_16x16x32_bf16 v[0:3], v[66:69], v[70:73], v[0:3]
	v_bfe_u32 v66, v4, 16, 1
	v_add3_u32 v66, v4, v66, s28
	ds_write_b16_d16_hi v76, v66 offset:0
	v_bfe_u32 v66, v5, 16, 1
	v_add3_u32 v66, v5, v66, s28
	ds_write_b16_d16_hi v76, v66 offset:272
	v_bfe_u32 v66, v6, 16, 1
	v_add3_u32 v66, v6, v66, s28
	ds_write_b16_d16_hi v76, v66 offset:544
	v_bfe_u32 v66, v7, 16, 1
	v_add3_u32 v66, v7, v66, s28
	ds_write_b16_d16_hi v76, v66 offset:816
	v_bfe_u32 v66, v42, 16, 1
	v_add3_u32 v66, v42, v66, s28
	ds_write_b16_d16_hi v76, v66 offset:32
	v_bfe_u32 v66, v43, 16, 1
	v_add3_u32 v66, v43, v66, s28
	ds_write_b16_d16_hi v76, v66 offset:304
	v_bfe_u32 v66, v44, 16, 1
	v_add3_u32 v66, v44, v66, s28
	ds_write_b16_d16_hi v76, v66 offset:576
	v_bfe_u32 v66, v45, 16, 1
	v_add3_u32 v66, v45, v66, s28
	ds_write_b16_d16_hi v76, v66 offset:848
	v_bfe_u32 v66, v46, 16, 1
	v_add3_u32 v66, v46, v66, s28
	ds_write_b16_d16_hi v76, v66 offset:64
	v_bfe_u32 v66, v47, 16, 1
	v_add3_u32 v66, v47, v66, s28
	ds_write_b16_d16_hi v76, v66 offset:336
	v_bfe_u32 v66, v48, 16, 1
	v_add3_u32 v66, v48, v66, s28
	ds_write_b16_d16_hi v76, v66 offset:608
	v_bfe_u32 v66, v49, 16, 1
	v_add3_u32 v66, v49, v66, s28
	ds_write_b16_d16_hi v76, v66 offset:880
	v_bfe_u32 v66, v50, 16, 1
	v_add3_u32 v66, v50, v66, s28
	ds_write_b16_d16_hi v76, v66 offset:96
	v_bfe_u32 v66, v51, 16, 1
	v_add3_u32 v66, v51, v66, s28
	ds_write_b16_d16_hi v76, v66 offset:368
	v_bfe_u32 v66, v52, 16, 1
	v_add3_u32 v66, v52, v66, s28
	ds_write_b16_d16_hi v76, v66 offset:640
	v_bfe_u32 v66, v53, 16, 1
	v_add3_u32 v66, v53, v66, s28
	ds_write_b16_d16_hi v76, v66 offset:912
	v_bfe_u32 v66, v54, 16, 1
	v_add3_u32 v66, v54, v66, s28
	ds_write_b16_d16_hi v76, v66 offset:128
	v_bfe_u32 v66, v55, 16, 1
	v_add3_u32 v66, v55, v66, s28
	ds_write_b16_d16_hi v76, v66 offset:400
	v_bfe_u32 v66, v56, 16, 1
	v_add3_u32 v66, v56, v66, s28
	ds_write_b16_d16_hi v76, v66 offset:672
	v_bfe_u32 v66, v57, 16, 1
	v_add3_u32 v66, v57, v66, s28
	ds_write_b16_d16_hi v76, v66 offset:944
	v_bfe_u32 v66, v58, 16, 1
	v_add3_u32 v66, v58, v66, s28
	ds_write_b16_d16_hi v76, v66 offset:160
	v_bfe_u32 v66, v59, 16, 1
	v_add3_u32 v66, v59, v66, s28
	ds_write_b16_d16_hi v76, v66 offset:432
	v_bfe_u32 v66, v60, 16, 1
	v_add3_u32 v66, v60, v66, s28
	ds_write_b16_d16_hi v76, v66 offset:704
	v_bfe_u32 v66, v61, 16, 1
	v_add3_u32 v66, v61, v66, s28
	ds_write_b16_d16_hi v76, v66 offset:976
	v_bfe_u32 v66, v62, 16, 1
	v_add3_u32 v66, v62, v66, s28
	ds_write_b16_d16_hi v76, v66 offset:192
	v_bfe_u32 v66, v63, 16, 1
	v_add3_u32 v66, v63, v66, s28
	ds_write_b16_d16_hi v76, v66 offset:464
	v_bfe_u32 v66, v64, 16, 1
	v_add3_u32 v66, v64, v66, s28
	ds_write_b16_d16_hi v76, v66 offset:736
	v_bfe_u32 v66, v65, 16, 1
	v_add3_u32 v66, v65, v66, s28
	ds_write_b16_d16_hi v76, v66 offset:1008
	v_bfe_u32 v66, v0, 16, 1
	v_add3_u32 v66, v0, v66, s28
	ds_write_b16_d16_hi v76, v66 offset:224
	v_bfe_u32 v66, v1, 16, 1
	v_add3_u32 v66, v1, v66, s28
	ds_write_b16_d16_hi v76, v66 offset:496
	v_bfe_u32 v66, v2, 16, 1
	v_add3_u32 v66, v2, v66, s28
	ds_write_b16_d16_hi v76, v66 offset:768
	v_bfe_u32 v66, v3, 16, 1
	v_add3_u32 v66, v3, v66, s28
	ds_write_b16_d16_hi v76, v66 offset:1040
	v_lshl_add_u64 v[96:97], v[78:79], 0, s[4:5]
	s_waitcnt lgkmcnt(0)
	ds_read_b128 v[80:83], v77 offset:0
	ds_read_b128 v[84:87], v77 offset:1088
	ds_read_b128 v[88:91], v77 offset:2176
	ds_read_b128 v[92:95], v77 offset:3264
	s_waitcnt lgkmcnt(3)
	global_store_dwordx4 v[96:97], v[80:83], off offset:0
	s_waitcnt lgkmcnt(2)
	global_store_dwordx4 v[96:97], v[84:87], off offset:1024
	s_waitcnt lgkmcnt(1)
	global_store_dwordx4 v[96:97], v[88:91], off offset:2048
	s_waitcnt lgkmcnt(0)
	global_store_dwordx4 v[96:97], v[92:95], off offset:3072
	s_and_saveexec_b64 s[4:5], s[44:45]
	s_cbranch_execz .LBB0_767
	s_add_i32 s2, s61, 0x9000
	v_mov_b32_e32 v0, 0
	s_mov_b32 s3, 0
